# k22 plus: non-temporal (nt) hint on the once-read prologue loads (f32 weights, x, p)
# baseline (speedup 1.0000x reference)
; __device__ __forceinline__ unsigned cvt_pk_bf16(float lo, float hi) { unsigned r; asm volatile("v_cvt_pk_bf16_f32 %0, %1, %2" : "=v"(r) : "v"(lo), "v"(hi)); return r; }
; #define GAS __attribute__((address_space(1)))
; #define LAS __attribute__((address_space(3)))
; #define LDS_WAIT() asm volatile("s_waitcnt lgkmcnt(0)" ::: "memory")
; __device__ __forceinline__ void tr_item(const float* W, int K, int N, const float* gain, bf16* WT, int k0, int n0, int dstrow, LAS float* scr, int lane, float f8s) {
;     const int c4 = lane & 15, r0 = lane >> 4;
; #pragma unroll 4
;     for (int i = 0; i < 16; ++i) { const int kk = 4 * i + r0; f32x4 v = *(const GAS f32x4*)(W + (size_t)(k0 + kk) * N + n0 + 4 * c4); if (gain) v = v * gain[k0 + kk];
;         *(LAS f32x4*)(scr + kk * 64 + 4 * (c4 ^ (2 * ((kk >> 3) & 7)))) = v; }
;     LDS_WAIT(); asm volatile("" ::: "memory");
;     const int c = lane & 7;
; #pragma unroll
;     for (int ps = 0; ps < 2; ++ps) { const int ng = (lane >> 3) + 8 * ps; f32x4 v[8];
; #pragma unroll
;         for (int j = 0; j < 8; ++j) v[j] = *(const LAS f32x4*)(scr + (8 * c + j) * 64 + 4 * (ng ^ (2 * c)));
; #pragma unroll
;         for (int i = 0; i < 4; ++i) {
;             if (f8s != 0.f) { v2u o8; o8.x = pg8::pack4_fp8(v[0][i] * f8s, v[1][i] * f8s, v[2][i] * f8s, v[3][i] * f8s); o8.y = pg8::pack4_fp8(v[4][i] * f8s, v[5][i] * f8s, v[6][i] * f8s, v[7][i] * f8s);
;                 *(GAS v2u*)((GAS unsigned char*)WT + (size_t)(dstrow + 4 * ng + i) * K + k0 + 8 * c) = o8; continue; }
;             v4u o; o.x = cvt_pk_bf16(v[0][i], v[1][i]); o.y = cvt_pk_bf16(v[2][i], v[3][i]); o.z = cvt_pk_bf16(v[4][i], v[5][i]); o.w = cvt_pk_bf16(v[6][i], v[7][i]);
;             *(GAS v4u*)(WT + (size_t)(dstrow + 4 * ng + i) * K + k0 + 8 * c) = o; } }
;     LDS_WAIT(); asm volatile("" ::: "memory");
.LBB0_85:
	v_add_u32_e32 v7, s1, v4
	v_add_u32_e32 v6, 0xffff5a00, v7
	v_add_u32_e32 v8, 0xffff5a04, v7
	v_add_u32_e32 v62, 0xffff5a08, v7
	v_add_u32_e32 v64, 0xffff5a0c, v7
	v_ashrrev_i32_e32 v7, 31, v6
	v_ashrrev_i32_e32 v9, 31, v8
	v_ashrrev_i32_e32 v63, 31, v62
	v_ashrrev_i32_e32 v65, 31, v64
	v_lshlrev_b64 v[6:7], 13, v[6:7]
	v_lshlrev_b64 v[8:9], 13, v[8:9]
	v_lshlrev_b64 v[62:63], 13, v[62:63]
	v_lshlrev_b64 v[64:65], 13, v[64:65]
	v_lshl_add_u64 v[6:7], v[2:3], 0, v[6:7]
	v_lshl_add_u64 v[66:67], v[2:3], 0, v[8:9]
	v_lshl_add_u64 v[68:69], v[2:3], 0, v[62:63]
	v_lshl_add_u64 v[70:71], v[2:3], 0, v[64:65]
	global_load_dwordx4 v[6:9], v[6:7], off nt
	s_nop 0
	global_load_dwordx4 v[62:65], v[66:67], off nt
	s_nop 0
	global_load_dwordx4 v[66:69], v[68:69], off nt
	s_nop 0
	global_load_dwordx4 v[70:73], v[70:71], off nt
	v_add_u32_e32 v14, s1, v12
	v_bitop3_b32 v108, v14, v11, 56 bitop3:0x6c
	v_add_u32_e32 v109, 4, v14
	v_add_u32_e32 v110, 8, v14
	v_add_u32_e32 v14, 12, v14
	s_add_i32 s1, s1, 16
	v_bitop3_b32 v109, v109, v11, 56 bitop3:0x6c
	v_bitop3_b32 v110, v110, v11, 56 bitop3:0x6c
	v_bitop3_b32 v14, v14, v11, 56 bitop3:0x6c
	s_cmp_lg_u32 s1, 64
	v_lshl_add_u32 v108, v108, 2, v5
	v_lshl_add_u32 v109, v109, 2, v5
	v_lshl_add_u32 v110, v110, 2, v5
	v_lshl_add_u32 v14, v14, 2, v5
	v_add_u32_e32 v5, 0x1000, v5
	s_waitcnt vmcnt(3)
	ds_write_b128 v108, v[6:9]
	s_waitcnt vmcnt(2)
	ds_write_b128 v109, v[62:65] offset:1024
	s_waitcnt vmcnt(1)
	ds_write_b128 v110, v[66:69] offset:2048
	s_waitcnt vmcnt(0)
	ds_write_b128 v14, v[70:73] offset:3072
	s_cbranch_scc1 .LBB0_85
	s_waitcnt lgkmcnt(0)
	ds_read_b128 v[2:5], v75
	ds_read_b128 v[6:9], v75 offset:256
	ds_read_b128 v[62:65], v75 offset:512
	ds_read_b128 v[66:69], v75 offset:768
	ds_read_b128 v[70:73], v75 offset:1024
	ds_read_b128 v[108:111], v75 offset:1280
	ds_read_b128 v[112:115], v75 offset:1536
	ds_read_b128 v[116:119], v75 offset:1792
	s_add_i32 s4, s0, 0xffff5a00
	v_lshl_add_u64 v[124:125], s[4:5], 1, v[16:17]
	v_add_lshl_u32 v14, s8, v13, 9
	s_waitcnt lgkmcnt(6)
	v_cvt_pk_bf16_f32 v120, v2, v6
	v_lshl_add_u64 v[126:127], v[124:125], 0, v[14:15]
	s_waitcnt lgkmcnt(4)
	v_cvt_pk_bf16_f32 v121, v62, v66
	s_waitcnt lgkmcnt(2)
	v_cvt_pk_bf16_f32 v122, v70, v108
	s_waitcnt lgkmcnt(0)
	v_cvt_pk_bf16_f32 v123, v112, v116
	global_store_dwordx4 v[126:127], v[120:123], off
	v_or_b32_e32 v2, 0x200, v14
	s_mov_b64 s[0:1], 0
	v_cvt_pk_bf16_f32 v120, v3, v7
	v_mov_b32_e32 v3, v15
	v_lshl_add_u64 v[2:3], v[124:125], 0, v[2:3]
	v_cvt_pk_bf16_f32 v121, v63, v67
	v_cvt_pk_bf16_f32 v122, v71, v109
	v_cvt_pk_bf16_f32 v123, v113, v117
	global_store_dwordx4 v[2:3], v[120:123], off
	v_or_b32_e32 v2, 0x400, v14
	v_mov_b32_e32 v3, v15
	v_cvt_pk_bf16_f32 v120, v4, v8
	v_cvt_pk_bf16_f32 v121, v64, v68
	v_cvt_pk_bf16_f32 v122, v72, v110
	v_cvt_pk_bf16_f32 v123, v114, v118
	v_lshl_add_u64 v[2:3], v[124:125], 0, v[2:3]
	global_store_dwordx4 v[2:3], v[120:123], off
	v_cvt_pk_bf16_f32 v2, v5, v9
	v_cvt_pk_bf16_f32 v3, v65, v69
	v_cvt_pk_bf16_f32 v4, v73, v111
	v_cvt_pk_bf16_f32 v5, v115, v119
	ds_read_b128 v[6:9], v77
	ds_read_b128 v[62:65], v77 offset:256
	ds_read_b128 v[66:69], v77 offset:512
	ds_read_b128 v[70:73], v77 offset:768
	ds_read_b128 v[108:111], v77 offset:1024
	ds_read_b128 v[112:115], v77 offset:1280
	ds_read_b128 v[116:119], v77 offset:1536
	ds_read_b128 v[120:123], v77 offset:1792
	v_or_b32_e32 v14, 0x600, v14
	v_lshl_add_u64 v[126:127], v[124:125], 0, v[14:15]
	v_add_lshl_u32 v14, s8, v76, 9
	global_store_dwordx4 v[126:127], v[2:5], off
	v_lshl_add_u64 v[126:127], v[124:125], 0, v[14:15]
	s_waitcnt lgkmcnt(6)
	v_cvt_pk_bf16_f32 v2, v6, v62
	s_waitcnt lgkmcnt(4)
	v_cvt_pk_bf16_f32 v3, v66, v70
	s_waitcnt lgkmcnt(2)
	v_cvt_pk_bf16_f32 v4, v108, v112
	s_waitcnt lgkmcnt(0)
	v_cvt_pk_bf16_f32 v5, v116, v120
	global_store_dwordx4 v[126:127], v[2:5], off
	v_or_b32_e32 v6, 0x200, v14
	s_nop 0
	v_cvt_pk_bf16_f32 v2, v7, v63
	v_mov_b32_e32 v7, v15
	v_lshl_add_u64 v[6:7], v[124:125], 0, v[6:7]
	v_cvt_pk_bf16_f32 v3, v67, v71
	v_cvt_pk_bf16_f32 v4, v109, v113
	v_cvt_pk_bf16_f32 v5, v117, v121
	global_store_dwordx4 v[6:7], v[2:5], off
	v_or_b32_e32 v6, 0x400, v14
	v_mov_b32_e32 v7, v15
	v_lshl_add_u64 v[6:7], v[124:125], 0, v[6:7]
	v_or_b32_e32 v14, 0x600, v14
	v_cvt_pk_bf16_f32 v2, v8, v64
	v_cvt_pk_bf16_f32 v3, v68, v72
	v_cvt_pk_bf16_f32 v4, v110, v114
	v_cvt_pk_bf16_f32 v5, v118, v122
	global_store_dwordx4 v[6:7], v[2:5], off
	v_lshl_add_u64 v[6:7], v[124:125], 0, v[14:15]
	s_nop 0
	v_cvt_pk_bf16_f32 v2, v9, v65
	v_cvt_pk_bf16_f32 v3, v69, v73
	v_cvt_pk_bf16_f32 v4, v111, v115
	v_cvt_pk_bf16_f32 v5, v119, v123
	global_store_dwordx4 v[6:7], v[2:5], off
	s_waitcnt lgkmcnt(0)

; #define GAS __attribute__((address_space(1)))
; #define LAS __attribute__((address_space(3)))
; __device__ __forceinline__ void tr_item(const float* W, int K, int N, const float* gain, bf16* WT, int k0, int n0, int dstrow, LAS float* scr, int lane, float f8s) {
;     ...
;     for (int i = 0; i < 16; ++i) { const int kk = 4 * i + r0; f32x4 v = *(const GAS f32x4*)(W + (size_t)(k0 + kk) * N + n0 + 4 * c4); if (gain) v = v * gain[k0 + kk];
;         *(LAS f32x4*)(scr + kk * 64 + 4 * (c4 ^ (2 * ((kk >> 3) & 7)))) = v; }
.LBB0_91:
	v_lshl_add_u64 v[130:131], v[64:65], 0, v[36:37]
	global_load_dwordx4 v[140:143], v[130:131], off nt
	v_lshl_add_u64 v[130:131], v[70:71], 0, v[36:37]
	global_load_dwordx4 v[144:147], v[130:131], off nt
	v_lshl_add_u64 v[130:131], v[66:67], 0, v[36:37]
	global_load_dwordx4 v[148:151], v[130:131], off nt
	v_lshl_add_u64 v[130:131], v[62:63], 0, v[36:37]
	global_load_dwordx4 v[152:155], v[130:131], off nt
	v_cndmask_b32_e64 v2, 0, 1, s[6:7]
	v_cmp_ne_u32_e64 s[0:1], 1, v2
	v_add_u32_e32 v136, s4, v12
	v_bitop3_b32 v132, v136, v11, 56 bitop3:0x6c
	v_lshl_add_u32 v132, v132, 2, v14
	v_add_u32_e32 v133, 4, v136
	v_bitop3_b32 v133, v133, v11, 56 bitop3:0x6c
	v_lshl_add_u32 v133, v133, 2, v14
	v_add_u32_e32 v134, 8, v136
	v_bitop3_b32 v134, v134, v11, 56 bitop3:0x6c
	v_lshl_add_u32 v134, v134, 2, v14
	v_add_u32_e32 v135, 12, v136
	v_bitop3_b32 v135, v135, v11, 56 bitop3:0x6c
	v_lshl_add_u32 v135, v135, 2, v14
	s_andn2_b64 vcc, exec, s[6:7]
	s_cbranch_vccnz .Ltrg1_nog
	global_load_dword v156, v[68:69], off
	global_load_dword v158, v[72:73], off
	global_load_dword v160, v[72:73], off offset:16
	global_load_dword v162, v[72:73], off offset:32
	s_waitcnt vmcnt(0)
	v_pk_mul_f32 v[142:143], v[142:143], v[156:157] op_sel_hi:[1,0]
	v_pk_mul_f32 v[140:141], v[140:141], v[156:157] op_sel_hi:[1,0]
	v_pk_mul_f32 v[146:147], v[146:147], v[158:159] op_sel_hi:[1,0]
	v_pk_mul_f32 v[144:145], v[144:145], v[158:159] op_sel_hi:[1,0]
	v_pk_mul_f32 v[150:151], v[150:151], v[160:161] op_sel_hi:[1,0]
	v_pk_mul_f32 v[148:149], v[148:149], v[160:161] op_sel_hi:[1,0]
	v_pk_mul_f32 v[154:155], v[154:155], v[162:163] op_sel_hi:[1,0]
	v_pk_mul_f32 v[152:153], v[152:153], v[162:163] op_sel_hi:[1,0]
	s_branch .Ltrg1_wr

; __device__ __forceinline__ unsigned cvt_pk_bf16(float lo, float hi) { unsigned r; asm volatile("v_cvt_pk_bf16_f32 %0, %1, %2" : "=v"(r) : "v"(lo), "v"(hi)); return r; }
; #define GAS __attribute__((address_space(1)))
; #define LAS __attribute__((address_space(3)))
; #define LDS_WAIT() asm volatile("s_waitcnt lgkmcnt(0)" ::: "memory")
; __device__ __forceinline__ void tr_item(const float* W, int K, int N, const float* gain, bf16* WT, int k0, int n0, int dstrow, LAS float* scr, int lane, float f8s) {
;     const int c4 = lane & 15, r0 = lane >> 4;
; #pragma unroll 4
;     for (int i = 0; i < 16; ++i) { const int kk = 4 * i + r0; f32x4 v = *(const GAS f32x4*)(W + (size_t)(k0 + kk) * N + n0 + 4 * c4); if (gain) v = v * gain[k0 + kk];
;         *(LAS f32x4*)(scr + kk * 64 + 4 * (c4 ^ (2 * ((kk >> 3) & 7)))) = v; }
;     LDS_WAIT(); asm volatile("" ::: "memory");
;     const int c = lane & 7;
; #pragma unroll
;     for (int ps = 0; ps < 2; ++ps) { const int ng = (lane >> 3) + 8 * ps; f32x4 v[8];
; #pragma unroll
;         for (int j = 0; j < 8; ++j) v[j] = *(const LAS f32x4*)(scr + (8 * c + j) * 64 + 4 * (ng ^ (2 * c)));
; #pragma unroll
;         for (int i = 0; i < 4; ++i) {
;             if (f8s != 0.f) { v2u o8; o8.x = pg8::pack4_fp8(v[0][i] * f8s, v[1][i] * f8s, v[2][i] * f8s, v[3][i] * f8s); o8.y = pg8::pack4_fp8(v[4][i] * f8s, v[5][i] * f8s, v[6][i] * f8s, v[7][i] * f8s);
;                 *(GAS v2u*)((GAS unsigned char*)WT + (size_t)(dstrow + 4 * ng + i) * K + k0 + 8 * c) = o8; continue; }
;             v4u o; o.x = cvt_pk_bf16(v[0][i], v[1][i]); o.y = cvt_pk_bf16(v[2][i], v[3][i]); o.z = cvt_pk_bf16(v[4][i], v[5][i]); o.w = cvt_pk_bf16(v[6][i], v[7][i]);
;             *(GAS v4u*)(WT + (size_t)(dstrow + 4 * ng + i) * K + k0 + 8 * c) = o; } }
;     LDS_WAIT(); asm volatile("" ::: "memory");
.LBB0_103:
	v_lshl_add_u64 v[62:63], v[8:9], 0, v[36:37]
	v_lshl_add_u64 v[66:67], v[6:7], 0, v[36:37]
	v_lshl_add_u64 v[70:71], v[4:5], 0, v[36:37]
	v_lshl_add_u64 v[108:109], v[2:3], 0, v[36:37]
	global_load_dwordx4 v[62:65], v[62:63], off nt
	s_nop 0
	global_load_dwordx4 v[66:69], v[66:67], off nt
	s_nop 0
	global_load_dwordx4 v[70:73], v[70:71], off nt
	s_nop 0
	global_load_dwordx4 v[108:111], v[108:109], off nt
	v_add_u32_e32 v112, s1, v12
	v_bitop3_b32 v113, v112, v11, 56 bitop3:0x6c
	v_add_u32_e32 v114, 4, v112
	v_add_u32_e32 v115, 8, v112
	v_add_u32_e32 v112, 12, v112
	s_add_i32 s1, s1, 16
	v_bitop3_b32 v114, v114, v11, 56 bitop3:0x6c
	v_bitop3_b32 v115, v115, v11, 56 bitop3:0x6c
	v_bitop3_b32 v112, v112, v11, 56 bitop3:0x6c
	v_lshl_add_u64 v[2:3], v[2:3], 0, s[50:51]
	v_lshl_add_u64 v[4:5], v[4:5], 0, s[50:51]
	v_lshl_add_u64 v[6:7], v[6:7], 0, s[50:51]
	v_lshl_add_u64 v[8:9], v[8:9], 0, s[50:51]
	s_cmp_lg_u32 s1, 64
	v_lshl_add_u32 v113, v113, 2, v14
	v_lshl_add_u32 v114, v114, 2, v14
	v_lshl_add_u32 v115, v115, 2, v14
	v_lshl_add_u32 v112, v112, 2, v14
	v_add_u32_e32 v14, 0x1000, v14
	s_waitcnt vmcnt(3)
	ds_write_b128 v113, v[62:65]
	s_waitcnt vmcnt(2)
	ds_write_b128 v114, v[66:69] offset:1024
	s_waitcnt vmcnt(1)
	ds_write_b128 v115, v[70:73] offset:2048
	s_waitcnt vmcnt(0)
	ds_write_b128 v112, v[108:111] offset:3072
	s_cbranch_scc1 .LBB0_103
	s_waitcnt lgkmcnt(0)
	ds_read_b128 v[2:5], v75
	ds_read_b128 v[6:9], v75 offset:256
	ds_read_b128 v[62:65], v75 offset:512
	ds_read_b128 v[66:69], v75 offset:768
	ds_read_b128 v[70:73], v75 offset:1024
	ds_read_b128 v[108:111], v75 offset:1280
	ds_read_b128 v[112:115], v75 offset:1536
	ds_read_b128 v[116:119], v75 offset:1792
	s_add_i32 s4, s0, 0xffff7800
	s_lshl_b32 s0, s10, 6
	s_and_b32 s8, s0, 0x7c0
	v_lshl_add_u64 v[124:125], s[4:5], 1, v[20:21]
	v_or_b32_e32 v14, s8, v13
	s_waitcnt lgkmcnt(6)
	v_cvt_pk_bf16_f32 v120, v2, v6
	v_mad_u64_u32 v[126:127], s[0:1], v14, s14, v[124:125]
	v_or_b32_e32 v2, 1, v14
	s_waitcnt lgkmcnt(4)
	v_cvt_pk_bf16_f32 v121, v62, v66
	s_waitcnt lgkmcnt(2)
	v_cvt_pk_bf16_f32 v122, v70, v108
	s_waitcnt lgkmcnt(0)
	v_cvt_pk_bf16_f32 v123, v112, v116
	global_store_dwordx4 v[126:127], v[120:123], off
	v_or_b32_e32 v6, 3, v14
	s_nop 0
	v_cvt_pk_bf16_f32 v120, v3, v7
	v_mad_u64_u32 v[2:3], s[0:1], v2, s14, v[124:125]
	v_cvt_pk_bf16_f32 v121, v63, v67
	v_cvt_pk_bf16_f32 v122, v71, v109
	v_cvt_pk_bf16_f32 v123, v113, v117
	global_store_dwordx4 v[2:3], v[120:123], off
	v_or_b32_e32 v2, 2, v14
	v_mad_u64_u32 v[2:3], s[0:1], v2, s14, v[124:125]
	v_mad_u64_u32 v[6:7], s[0:1], v6, s14, v[124:125]
	v_cvt_pk_bf16_f32 v120, v4, v8
	v_cvt_pk_bf16_f32 v121, v64, v68
	v_cvt_pk_bf16_f32 v122, v72, v110
	v_cvt_pk_bf16_f32 v123, v114, v118
	global_store_dwordx4 v[2:3], v[120:123], off
	v_cvt_pk_bf16_f32 v2, v5, v9
	v_cvt_pk_bf16_f32 v3, v65, v69
	v_cvt_pk_bf16_f32 v4, v73, v111
	v_cvt_pk_bf16_f32 v5, v115, v119
	global_store_dwordx4 v[6:7], v[2:5], off
	ds_read_b128 v[2:5], v77
	ds_read_b128 v[6:9], v77 offset:256
	ds_read_b128 v[62:65], v77 offset:512
	ds_read_b128 v[66:69], v77 offset:768
	ds_read_b128 v[70:73], v77 offset:1024
	ds_read_b128 v[108:111], v77 offset:1280
	ds_read_b128 v[112:115], v77 offset:1536
	ds_read_b128 v[116:119], v77 offset:1792
	v_add_u32_e32 v14, s8, v76
	s_waitcnt lgkmcnt(6)
	v_cvt_pk_bf16_f32 v120, v2, v6
	v_mad_u64_u32 v[126:127], s[0:1], v14, s14, v[124:125]
	v_or_b32_e32 v2, 1, v14
	s_waitcnt lgkmcnt(4)
	v_cvt_pk_bf16_f32 v121, v62, v66
	s_waitcnt lgkmcnt(2)
	v_cvt_pk_bf16_f32 v122, v70, v108
	s_waitcnt lgkmcnt(0)
	v_cvt_pk_bf16_f32 v123, v112, v116
	global_store_dwordx4 v[126:127], v[120:123], off
	v_or_b32_e32 v6, 3, v14
	s_nop 0
	v_cvt_pk_bf16_f32 v120, v3, v7
	v_mad_u64_u32 v[2:3], s[0:1], v2, s14, v[124:125]
	v_cvt_pk_bf16_f32 v121, v63, v67
	v_cvt_pk_bf16_f32 v122, v71, v109
	v_cvt_pk_bf16_f32 v123, v113, v117
	global_store_dwordx4 v[2:3], v[120:123], off
	v_or_b32_e32 v2, 2, v14
	v_mad_u64_u32 v[2:3], s[0:1], v2, s14, v[124:125]
	v_mad_u64_u32 v[6:7], s[0:1], v6, s14, v[124:125]
	v_cvt_pk_bf16_f32 v120, v4, v8
	v_cvt_pk_bf16_f32 v121, v64, v68
	v_cvt_pk_bf16_f32 v122, v72, v110
	v_cvt_pk_bf16_f32 v123, v114, v118
	global_store_dwordx4 v[2:3], v[120:123], off
	v_cvt_pk_bf16_f32 v2, v5, v9
	v_cvt_pk_bf16_f32 v3, v65, v69
	v_cvt_pk_bf16_f32 v4, v73, v111
	v_cvt_pk_bf16_f32 v5, v115, v119
	global_store_dwordx4 v[6:7], v[2:5], off
	s_waitcnt lgkmcnt(0)

; #define GAS __attribute__((address_space(1)))
; #define LAS __attribute__((address_space(3)))
; __device__ __forceinline__ void tr_item(const float* W, int K, int N, const float* gain, bf16* WT, int k0, int n0, int dstrow, LAS float* scr, int lane, float f8s) {
;     ...
;     for (int i = 0; i < 16; ++i) { const int kk = 4 * i + r0; f32x4 v = *(const GAS f32x4*)(W + (size_t)(k0 + kk) * N + n0 + 4 * c4); if (gain) v = v * gain[k0 + kk];
;         *(LAS f32x4*)(scr + kk * 64 + 4 * (c4 ^ (2 * ((kk >> 3) & 7)))) = v; }
.LBB0_109:
	v_lshl_add_u64 v[130:131], v[64:65], 0, s[4:5]
	global_load_dwordx4 v[140:143], v[130:131], off nt
	v_lshl_add_u64 v[130:131], v[70:71], 0, s[4:5]
	global_load_dwordx4 v[144:147], v[130:131], off nt
	v_lshl_add_u64 v[130:131], v[66:67], 0, s[4:5]
	global_load_dwordx4 v[148:151], v[130:131], off nt
	v_lshl_add_u64 v[130:131], v[62:63], 0, s[4:5]
	global_load_dwordx4 v[152:155], v[130:131], off nt
	v_cndmask_b32_e64 v2, 0, 1, s[18:19]
	v_cmp_ne_u32_e64 s[0:1], 1, v2
	v_add_u32_e32 v136, s17, v12
	v_bitop3_b32 v132, v136, v11, 56 bitop3:0x6c
	v_lshl_add_u32 v132, v132, 2, v14
	v_add_u32_e32 v133, 4, v136
	v_bitop3_b32 v133, v133, v11, 56 bitop3:0x6c
	v_lshl_add_u32 v133, v133, 2, v14
	v_add_u32_e32 v134, 8, v136
	v_bitop3_b32 v134, v134, v11, 56 bitop3:0x6c
	v_lshl_add_u32 v134, v134, 2, v14
	v_add_u32_e32 v135, 12, v136
	v_bitop3_b32 v135, v135, v11, 56 bitop3:0x6c
	v_lshl_add_u32 v135, v135, 2, v14
	s_andn2_b64 vcc, exec, s[18:19]
	s_cbranch_vccnz .Ltrg2_nog
	global_load_dword v156, v[68:69], off offset:-32
	global_load_dword v158, v[68:69], off offset:-16
	global_load_dword v160, v[68:69], off
	global_load_dword v162, v[68:69], off offset:16
	s_waitcnt vmcnt(0)
	v_pk_mul_f32 v[142:143], v[142:143], v[156:157] op_sel_hi:[1,0]
	v_pk_mul_f32 v[140:141], v[140:141], v[156:157] op_sel_hi:[1,0]
	v_pk_mul_f32 v[146:147], v[146:147], v[158:159] op_sel_hi:[1,0]
	v_pk_mul_f32 v[144:145], v[144:145], v[158:159] op_sel_hi:[1,0]
	v_pk_mul_f32 v[150:151], v[150:151], v[160:161] op_sel_hi:[1,0]
	v_pk_mul_f32 v[148:149], v[148:149], v[160:161] op_sel_hi:[1,0]
	v_pk_mul_f32 v[154:155], v[154:155], v[162:163] op_sel_hi:[1,0]
	v_pk_mul_f32 v[152:153], v[152:153], v[162:163] op_sel_hi:[1,0]
	s_branch .Ltrg2_wr

; #define GAS __attribute__((address_space(1)))
; #define LAS __attribute__((address_space(3)))
; __device__ __forceinline__ void tr_item(const float* W, int K, int N, const float* gain, bf16* WT, int k0, int n0, int dstrow, LAS float* scr, int lane, float f8s) {
;     ...
;     for (int i = 0; i < 16; ++i) { const int kk = 4 * i + r0; f32x4 v = *(const GAS f32x4*)(W + (size_t)(k0 + kk) * N + n0 + 4 * c4); if (gain) v = v * gain[k0 + kk];
;         *(LAS f32x4*)(scr + kk * 64 + 4 * (c4 ^ (2 * ((kk >> 3) & 7)))) = v; }
.LBB0_135:
	v_lshl_add_u64 v[130:131], v[64:65], 0, v[36:37]
	global_load_dwordx4 v[140:143], v[130:131], off nt
	v_lshl_add_u64 v[130:131], v[70:71], 0, v[36:37]
	global_load_dwordx4 v[144:147], v[130:131], off nt
	v_lshl_add_u64 v[130:131], v[66:67], 0, v[36:37]
	global_load_dwordx4 v[148:151], v[130:131], off nt
	v_lshl_add_u64 v[130:131], v[62:63], 0, v[36:37]
	global_load_dwordx4 v[152:155], v[130:131], off nt
	v_cndmask_b32_e64 v2, 0, 1, s[8:9]
	v_cmp_ne_u32_e64 s[0:1], 1, v2
	v_add_u32_e32 v136, s4, v12
	v_bitop3_b32 v132, v136, v11, 56 bitop3:0x6c
	v_lshl_add_u32 v132, v132, 2, v14
	v_add_u32_e32 v133, 4, v136
	v_bitop3_b32 v133, v133, v11, 56 bitop3:0x6c
	v_lshl_add_u32 v133, v133, 2, v14
	v_add_u32_e32 v134, 8, v136
	v_bitop3_b32 v134, v134, v11, 56 bitop3:0x6c
	v_lshl_add_u32 v134, v134, 2, v14
	v_add_u32_e32 v135, 12, v136
	v_bitop3_b32 v135, v135, v11, 56 bitop3:0x6c
	v_lshl_add_u32 v135, v135, 2, v14
	s_andn2_b64 vcc, exec, s[8:9]
	s_cbranch_vccnz .Ltrg4_nog
	global_load_dword v156, v[68:69], off
	global_load_dword v158, v[72:73], off
	global_load_dword v160, v[72:73], off offset:16
	global_load_dword v162, v[72:73], off offset:32
	s_waitcnt vmcnt(0)
	v_pk_mul_f32 v[142:143], v[142:143], v[156:157] op_sel_hi:[1,0]
	v_pk_mul_f32 v[140:141], v[140:141], v[156:157] op_sel_hi:[1,0]
	v_pk_mul_f32 v[146:147], v[146:147], v[158:159] op_sel_hi:[1,0]
	v_pk_mul_f32 v[144:145], v[144:145], v[158:159] op_sel_hi:[1,0]
	v_pk_mul_f32 v[150:151], v[150:151], v[160:161] op_sel_hi:[1,0]
	v_pk_mul_f32 v[148:149], v[148:149], v[160:161] op_sel_hi:[1,0]
	v_pk_mul_f32 v[154:155], v[154:155], v[162:163] op_sel_hi:[1,0]
	v_pk_mul_f32 v[152:153], v[152:153], v[162:163] op_sel_hi:[1,0]
	s_branch .Ltrg4_wr

; __device__ __forceinline__ unsigned cvt_pk_bf16(float lo, float hi) { unsigned r; asm volatile("v_cvt_pk_bf16_f32 %0, %1, %2" : "=v"(r) : "v"(lo), "v"(hi)); return r; }
; #define GAS __attribute__((address_space(1)))
; #define LAS __attribute__((address_space(3)))
; #define LDS_WAIT() asm volatile("s_waitcnt lgkmcnt(0)" ::: "memory")
; __device__ __forceinline__ void tr_item(const float* W, int K, int N, const float* gain, bf16* WT, int k0, int n0, int dstrow, LAS float* scr, int lane, float f8s) {
;     const int c4 = lane & 15, r0 = lane >> 4;
; #pragma unroll 4
;     for (int i = 0; i < 16; ++i) { const int kk = 4 * i + r0; f32x4 v = *(const GAS f32x4*)(W + (size_t)(k0 + kk) * N + n0 + 4 * c4); if (gain) v = v * gain[k0 + kk];
;         *(LAS f32x4*)(scr + kk * 64 + 4 * (c4 ^ (2 * ((kk >> 3) & 7)))) = v; }
;     LDS_WAIT(); asm volatile("" ::: "memory");
;     const int c = lane & 7;
; #pragma unroll
;     for (int ps = 0; ps < 2; ++ps) { const int ng = (lane >> 3) + 8 * ps; f32x4 v[8];
; #pragma unroll
;         for (int j = 0; j < 8; ++j) v[j] = *(const LAS f32x4*)(scr + (8 * c + j) * 64 + 4 * (ng ^ (2 * c)));
; #pragma unroll
;         for (int i = 0; i < 4; ++i) {
;             if (f8s != 0.f) { v2u o8; o8.x = pg8::pack4_fp8(v[0][i] * f8s, v[1][i] * f8s, v[2][i] * f8s, v[3][i] * f8s); o8.y = pg8::pack4_fp8(v[4][i] * f8s, v[5][i] * f8s, v[6][i] * f8s, v[7][i] * f8s);
;                 *(GAS v2u*)((GAS unsigned char*)WT + (size_t)(dstrow + 4 * ng + i) * K + k0 + 8 * c) = o8; continue; }
;             v4u o; o.x = cvt_pk_bf16(v[0][i], v[1][i]); o.y = cvt_pk_bf16(v[2][i], v[3][i]); o.z = cvt_pk_bf16(v[4][i], v[5][i]); o.w = cvt_pk_bf16(v[6][i], v[7][i]);
;             *(GAS v4u*)(WT + (size_t)(dstrow + 4 * ng + i) * K + k0 + 8 * c) = o; } }
;     LDS_WAIT(); asm volatile("" ::: "memory");
.LBB0_147:
	v_lshl_add_u64 v[62:63], v[8:9], 0, v[36:37]
	v_lshl_add_u64 v[66:67], v[6:7], 0, v[36:37]
	v_lshl_add_u64 v[70:71], v[4:5], 0, v[36:37]
	v_lshl_add_u64 v[108:109], v[2:3], 0, v[36:37]
	global_load_dwordx4 v[62:65], v[62:63], off nt
	s_nop 0
	global_load_dwordx4 v[66:69], v[66:67], off nt
	s_nop 0
	global_load_dwordx4 v[70:73], v[70:71], off nt
	s_nop 0
	global_load_dwordx4 v[108:111], v[108:109], off nt
	v_add_u32_e32 v112, s1, v12
	v_bitop3_b32 v113, v112, v11, 56 bitop3:0x6c
	v_add_u32_e32 v114, 4, v112
	v_add_u32_e32 v115, 8, v112
	v_add_u32_e32 v112, 12, v112
	s_add_i32 s1, s1, 16
	v_bitop3_b32 v114, v114, v11, 56 bitop3:0x6c
	v_bitop3_b32 v115, v115, v11, 56 bitop3:0x6c
	v_bitop3_b32 v112, v112, v11, 56 bitop3:0x6c
	v_lshl_add_u64 v[2:3], v[2:3], 0, s[76:77]
	v_lshl_add_u64 v[4:5], v[4:5], 0, s[76:77]
	v_lshl_add_u64 v[6:7], v[6:7], 0, s[76:77]
	v_lshl_add_u64 v[8:9], v[8:9], 0, s[76:77]
	s_cmp_lg_u32 s1, 64
	v_lshl_add_u32 v113, v113, 2, v14
	v_lshl_add_u32 v114, v114, 2, v14
	v_lshl_add_u32 v115, v115, 2, v14
	v_lshl_add_u32 v112, v112, 2, v14
	v_add_u32_e32 v14, 0x1000, v14
	s_waitcnt vmcnt(3)
	ds_write_b128 v113, v[62:65]
	s_waitcnt vmcnt(2)
	ds_write_b128 v114, v[66:69] offset:1024
	s_waitcnt vmcnt(1)
	ds_write_b128 v115, v[70:73] offset:2048
	s_waitcnt vmcnt(0)
	ds_write_b128 v112, v[108:111] offset:3072
	s_cbranch_scc1 .LBB0_147
	s_waitcnt lgkmcnt(0)
	s_add_i32 s4, s0, 0xffff5c00
	s_lshl_b32 s0, s10, 6
	ds_read_b128 v[2:5], v75
	ds_read_b128 v[6:9], v75 offset:256
	ds_read_b128 v[62:65], v75 offset:512
	ds_read_b128 v[66:69], v75 offset:768
	ds_read_b128 v[70:73], v75 offset:1024
	ds_read_b128 v[108:111], v75 offset:1280
	ds_read_b128 v[112:115], v75 offset:1536
	ds_read_b128 v[116:119], v75 offset:1792
	s_and_b32 s0, s0, 0x3c0
	v_or_b32_e32 v14, s0, v13
	v_lshl_add_u64 v[124:125], s[4:5], 1, v[26:27]
	v_lshlrev_b32_e32 v14, 11, v14
	s_waitcnt lgkmcnt(6)
	v_cvt_pk_bf16_f32 v120, v2, v6
	v_lshl_add_u64 v[126:127], v[124:125], 0, v[14:15]
	s_waitcnt lgkmcnt(4)
	v_cvt_pk_bf16_f32 v121, v62, v66
	s_waitcnt lgkmcnt(2)
	v_cvt_pk_bf16_f32 v122, v70, v108
	s_waitcnt lgkmcnt(0)
	v_cvt_pk_bf16_f32 v123, v112, v116
	global_store_dwordx4 v[126:127], v[120:123], off
	v_or_b32_e32 v2, 0x800, v14
	s_nop 0
	v_cvt_pk_bf16_f32 v120, v3, v7
	v_mov_b32_e32 v3, v15
	v_lshl_add_u64 v[2:3], v[124:125], 0, v[2:3]
	v_cvt_pk_bf16_f32 v121, v63, v67
	v_cvt_pk_bf16_f32 v122, v71, v109
	v_cvt_pk_bf16_f32 v123, v113, v117
	global_store_dwordx4 v[2:3], v[120:123], off
	v_or_b32_e32 v2, 0x1000, v14
	v_mov_b32_e32 v3, v15
	v_cvt_pk_bf16_f32 v120, v4, v8
	v_cvt_pk_bf16_f32 v121, v64, v68
	v_cvt_pk_bf16_f32 v122, v72, v110
	v_cvt_pk_bf16_f32 v123, v114, v118
	v_lshl_add_u64 v[2:3], v[124:125], 0, v[2:3]
	global_store_dwordx4 v[2:3], v[120:123], off
	v_cvt_pk_bf16_f32 v2, v5, v9
	v_cvt_pk_bf16_f32 v3, v65, v69
	v_cvt_pk_bf16_f32 v4, v73, v111
	v_cvt_pk_bf16_f32 v5, v115, v119
	ds_read_b128 v[6:9], v77
	ds_read_b128 v[62:65], v77 offset:256
	ds_read_b128 v[66:69], v77 offset:512
	ds_read_b128 v[70:73], v77 offset:768
	ds_read_b128 v[108:111], v77 offset:1024
	ds_read_b128 v[112:115], v77 offset:1280
	ds_read_b128 v[116:119], v77 offset:1536
	ds_read_b128 v[120:123], v77 offset:1792
	v_or_b32_e32 v14, 0x1800, v14
	v_lshl_add_u64 v[126:127], v[124:125], 0, v[14:15]
	v_add_lshl_u32 v14, s0, v76, 11
	global_store_dwordx4 v[126:127], v[2:5], off
	v_lshl_add_u64 v[126:127], v[124:125], 0, v[14:15]
	s_waitcnt lgkmcnt(6)
	v_cvt_pk_bf16_f32 v2, v6, v62
	s_waitcnt lgkmcnt(4)
	v_cvt_pk_bf16_f32 v3, v66, v70
	s_waitcnt lgkmcnt(2)
	v_cvt_pk_bf16_f32 v4, v108, v112
	s_waitcnt lgkmcnt(0)
	v_cvt_pk_bf16_f32 v5, v116, v120
	global_store_dwordx4 v[126:127], v[2:5], off
	v_or_b32_e32 v6, 0x800, v14
	s_nop 0
	v_cvt_pk_bf16_f32 v2, v7, v63
	v_mov_b32_e32 v7, v15
	v_lshl_add_u64 v[6:7], v[124:125], 0, v[6:7]
	v_cvt_pk_bf16_f32 v3, v67, v71
	v_cvt_pk_bf16_f32 v4, v109, v113
	v_cvt_pk_bf16_f32 v5, v117, v121
	global_store_dwordx4 v[6:7], v[2:5], off
	v_or_b32_e32 v6, 0x1000, v14
	v_mov_b32_e32 v7, v15
	v_lshl_add_u64 v[6:7], v[124:125], 0, v[6:7]
	v_or_b32_e32 v14, 0x1800, v14
	v_cvt_pk_bf16_f32 v2, v8, v64
	v_cvt_pk_bf16_f32 v3, v68, v72
	v_cvt_pk_bf16_f32 v4, v110, v114
	v_cvt_pk_bf16_f32 v5, v118, v122
	global_store_dwordx4 v[6:7], v[2:5], off
	v_lshl_add_u64 v[6:7], v[124:125], 0, v[14:15]
	s_nop 0
	v_cvt_pk_bf16_f32 v2, v9, v65
	v_cvt_pk_bf16_f32 v3, v69, v73
	v_cvt_pk_bf16_f32 v4, v111, v115
	v_cvt_pk_bf16_f32 v5, v119, v123
	global_store_dwordx4 v[6:7], v[2:5], off
	s_waitcnt lgkmcnt(0)

; #define GAS __attribute__((address_space(1)))
; #define LAS __attribute__((address_space(3)))
; __device__ __forceinline__ void tr_item(const float* W, int K, int N, const float* gain, bf16* WT, int k0, int n0, int dstrow, LAS float* scr, int lane, float f8s) {
;     ...
;     for (int i = 0; i < 16; ++i) { const int kk = 4 * i + r0; f32x4 v = *(const GAS f32x4*)(W + (size_t)(k0 + kk) * N + n0 + 4 * c4); if (gain) v = v * gain[k0 + kk];
;         *(LAS f32x4*)(scr + kk * 64 + 4 * (c4 ^ (2 * ((kk >> 3) & 7)))) = v; }
.LBB0_153:
	v_lshl_add_u64 v[130:131], v[64:65], 0, v[36:37]
	global_load_dwordx4 v[140:143], v[130:131], off nt
	v_lshl_add_u64 v[130:131], v[70:71], 0, v[36:37]
	global_load_dwordx4 v[144:147], v[130:131], off nt
	v_lshl_add_u64 v[130:131], v[66:67], 0, v[36:37]
	global_load_dwordx4 v[148:151], v[130:131], off nt
	v_lshl_add_u64 v[130:131], v[62:63], 0, v[36:37]
	global_load_dwordx4 v[152:155], v[130:131], off nt
	v_cndmask_b32_e64 v2, 0, 1, s[28:29]
	v_cmp_ne_u32_e64 s[0:1], 1, v2
	v_add_u32_e32 v136, s4, v12
	v_bitop3_b32 v132, v136, v11, 56 bitop3:0x6c
	v_lshl_add_u32 v132, v132, 2, v14
	v_add_u32_e32 v133, 4, v136
	v_bitop3_b32 v133, v133, v11, 56 bitop3:0x6c
	v_lshl_add_u32 v133, v133, 2, v14
	v_add_u32_e32 v134, 8, v136
	v_bitop3_b32 v134, v134, v11, 56 bitop3:0x6c
	v_lshl_add_u32 v134, v134, 2, v14
	v_add_u32_e32 v135, 12, v136
	v_bitop3_b32 v135, v135, v11, 56 bitop3:0x6c
	v_lshl_add_u32 v135, v135, 2, v14
	s_andn2_b64 vcc, exec, s[28:29]
	s_cbranch_vccnz .Ltrg5_nog
	global_load_dword v156, v[68:69], off
	global_load_dword v158, v[72:73], off
	global_load_dword v160, v[72:73], off offset:16
	global_load_dword v162, v[72:73], off offset:32
	s_waitcnt vmcnt(0)
	v_pk_mul_f32 v[142:143], v[142:143], v[156:157] op_sel_hi:[1,0]
	v_pk_mul_f32 v[140:141], v[140:141], v[156:157] op_sel_hi:[1,0]
	v_pk_mul_f32 v[146:147], v[146:147], v[158:159] op_sel_hi:[1,0]
	v_pk_mul_f32 v[144:145], v[144:145], v[158:159] op_sel_hi:[1,0]
	v_pk_mul_f32 v[150:151], v[150:151], v[160:161] op_sel_hi:[1,0]
	v_pk_mul_f32 v[148:149], v[148:149], v[160:161] op_sel_hi:[1,0]
	v_pk_mul_f32 v[154:155], v[154:155], v[162:163] op_sel_hi:[1,0]
	v_pk_mul_f32 v[152:153], v[152:153], v[162:163] op_sel_hi:[1,0]
	s_branch .Ltrg5_wr

; __device__ __forceinline__ unsigned cvt_pk_bf16(float lo, float hi) { unsigned r; asm volatile("v_cvt_pk_bf16_f32 %0, %1, %2" : "=v"(r) : "v"(lo), "v"(hi)); return r; }
; #define GAS __attribute__((address_space(1)))
; #define LAS __attribute__((address_space(3)))
; #define LDS_WAIT() asm volatile("s_waitcnt lgkmcnt(0)" ::: "memory")
; __device__ __forceinline__ void tr_item(const float* W, int K, int N, const float* gain, bf16* WT, int k0, int n0, int dstrow, LAS float* scr, int lane, float f8s) {
;     const int c4 = lane & 15, r0 = lane >> 4;
; #pragma unroll 4
;     for (int i = 0; i < 16; ++i) { const int kk = 4 * i + r0; f32x4 v = *(const GAS f32x4*)(W + (size_t)(k0 + kk) * N + n0 + 4 * c4); if (gain) v = v * gain[k0 + kk];
;         *(LAS f32x4*)(scr + kk * 64 + 4 * (c4 ^ (2 * ((kk >> 3) & 7)))) = v; }
;     LDS_WAIT(); asm volatile("" ::: "memory");
;     const int c = lane & 7;
; #pragma unroll
;     for (int ps = 0; ps < 2; ++ps) { const int ng = (lane >> 3) + 8 * ps; f32x4 v[8];
; #pragma unroll
;         for (int j = 0; j < 8; ++j) v[j] = *(const LAS f32x4*)(scr + (8 * c + j) * 64 + 4 * (ng ^ (2 * c)));
; #pragma unroll
;         for (int i = 0; i < 4; ++i) {
;             if (f8s != 0.f) { v2u o8; o8.x = pg8::pack4_fp8(v[0][i] * f8s, v[1][i] * f8s, v[2][i] * f8s, v[3][i] * f8s); o8.y = pg8::pack4_fp8(v[4][i] * f8s, v[5][i] * f8s, v[6][i] * f8s, v[7][i] * f8s);
;                 *(GAS v2u*)((GAS unsigned char*)WT + (size_t)(dstrow + 4 * ng + i) * K + k0 + 8 * c) = o8; continue; }
;             v4u o; o.x = cvt_pk_bf16(v[0][i], v[1][i]); o.y = cvt_pk_bf16(v[2][i], v[3][i]); o.z = cvt_pk_bf16(v[4][i], v[5][i]); o.w = cvt_pk_bf16(v[6][i], v[7][i]);
;             *(GAS v4u*)(WT + (size_t)(dstrow + 4 * ng + i) * K + k0 + 8 * c) = o; } }
;     LDS_WAIT(); asm volatile("" ::: "memory");
.LBB0_165:
	v_lshl_add_u64 v[62:63], v[8:9], 0, v[36:37]
	v_lshl_add_u64 v[66:67], v[6:7], 0, v[36:37]
	v_lshl_add_u64 v[70:71], v[4:5], 0, v[36:37]
	v_lshl_add_u64 v[108:109], v[2:3], 0, v[36:37]
	global_load_dwordx4 v[62:65], v[62:63], off nt
	s_nop 0
	global_load_dwordx4 v[66:69], v[66:67], off nt
	s_nop 0
	global_load_dwordx4 v[70:73], v[70:71], off nt
	s_nop 0
	global_load_dwordx4 v[108:111], v[108:109], off nt
	v_add_u32_e32 v112, s1, v12
	v_bitop3_b32 v113, v112, v11, 56 bitop3:0x6c
	v_add_u32_e32 v114, 4, v112
	v_add_u32_e32 v115, 8, v112
	v_add_u32_e32 v112, 12, v112
	s_add_i32 s1, s1, 16
	v_bitop3_b32 v114, v114, v11, 56 bitop3:0x6c
	v_bitop3_b32 v115, v115, v11, 56 bitop3:0x6c
	v_bitop3_b32 v112, v112, v11, 56 bitop3:0x6c
	v_lshl_add_u64 v[2:3], v[2:3], 0, s[50:51]
	v_lshl_add_u64 v[4:5], v[4:5], 0, s[50:51]
	v_lshl_add_u64 v[6:7], v[6:7], 0, s[50:51]
	v_lshl_add_u64 v[8:9], v[8:9], 0, s[50:51]
	s_cmp_lg_u32 s1, 64
	v_lshl_add_u32 v113, v113, 2, v14
	v_lshl_add_u32 v114, v114, 2, v14
	v_lshl_add_u32 v115, v115, 2, v14
	v_lshl_add_u32 v112, v112, 2, v14
	v_add_u32_e32 v14, 0x1000, v14
	s_waitcnt vmcnt(3)
	ds_write_b128 v113, v[62:65]
	s_waitcnt vmcnt(2)
	ds_write_b128 v114, v[66:69] offset:1024
	s_waitcnt vmcnt(1)
	ds_write_b128 v115, v[70:73] offset:2048
	s_waitcnt vmcnt(0)
	ds_write_b128 v112, v[108:111] offset:3072
	s_cbranch_scc1 .LBB0_165
	s_waitcnt lgkmcnt(0)
	ds_read_b128 v[2:5], v75
	ds_read_b128 v[6:9], v75 offset:256
	ds_read_b128 v[62:65], v75 offset:512
	ds_read_b128 v[66:69], v75 offset:768
	ds_read_b128 v[70:73], v75 offset:1024
	ds_read_b128 v[108:111], v75 offset:1280
	ds_read_b128 v[112:115], v75 offset:1536
	ds_read_b128 v[116:119], v75 offset:1792
	s_add_i32 s4, s0, 0xffffd400
	s_lshl_b32 s0, s10, 6
	s_and_b32 s8, s0, 0x7c0
	v_lshl_add_u64 v[124:125], s[4:5], 1, v[30:31]
	v_or_b32_e32 v14, s8, v13
	s_waitcnt lgkmcnt(6)
	v_cvt_pk_bf16_f32 v120, v2, v6
	v_mad_u64_u32 v[126:127], s[0:1], v14, s14, v[124:125]
	v_or_b32_e32 v2, 1, v14
	s_waitcnt lgkmcnt(4)
	v_cvt_pk_bf16_f32 v121, v62, v66
	s_waitcnt lgkmcnt(2)
	v_cvt_pk_bf16_f32 v122, v70, v108
	s_waitcnt lgkmcnt(0)
	v_cvt_pk_bf16_f32 v123, v112, v116
	global_store_dwordx4 v[126:127], v[120:123], off
	v_or_b32_e32 v6, 3, v14
	s_nop 0
	v_cvt_pk_bf16_f32 v120, v3, v7
	v_mad_u64_u32 v[2:3], s[0:1], v2, s14, v[124:125]
	v_cvt_pk_bf16_f32 v121, v63, v67
	v_cvt_pk_bf16_f32 v122, v71, v109
	v_cvt_pk_bf16_f32 v123, v113, v117
	global_store_dwordx4 v[2:3], v[120:123], off
	v_or_b32_e32 v2, 2, v14
	v_mad_u64_u32 v[2:3], s[0:1], v2, s14, v[124:125]
	v_mad_u64_u32 v[6:7], s[0:1], v6, s14, v[124:125]
	v_cvt_pk_bf16_f32 v120, v4, v8
	v_cvt_pk_bf16_f32 v121, v64, v68
	v_cvt_pk_bf16_f32 v122, v72, v110
	v_cvt_pk_bf16_f32 v123, v114, v118
	global_store_dwordx4 v[2:3], v[120:123], off
	v_cvt_pk_bf16_f32 v2, v5, v9
	v_cvt_pk_bf16_f32 v3, v65, v69
	v_cvt_pk_bf16_f32 v4, v73, v111
	v_cvt_pk_bf16_f32 v5, v115, v119
	global_store_dwordx4 v[6:7], v[2:5], off
	ds_read_b128 v[2:5], v77
	ds_read_b128 v[6:9], v77 offset:256
	ds_read_b128 v[62:65], v77 offset:512
	ds_read_b128 v[66:69], v77 offset:768
	ds_read_b128 v[70:73], v77 offset:1024
	ds_read_b128 v[108:111], v77 offset:1280
	ds_read_b128 v[112:115], v77 offset:1536
	ds_read_b128 v[116:119], v77 offset:1792
	v_add_u32_e32 v14, s8, v76
	s_waitcnt lgkmcnt(6)
	v_cvt_pk_bf16_f32 v120, v2, v6
	v_mad_u64_u32 v[126:127], s[0:1], v14, s14, v[124:125]
	v_or_b32_e32 v2, 1, v14
	s_waitcnt lgkmcnt(4)
	v_cvt_pk_bf16_f32 v121, v62, v66
	s_waitcnt lgkmcnt(2)
	v_cvt_pk_bf16_f32 v122, v70, v108
	s_waitcnt lgkmcnt(0)
	v_cvt_pk_bf16_f32 v123, v112, v116
	global_store_dwordx4 v[126:127], v[120:123], off
	v_or_b32_e32 v6, 3, v14
	s_nop 0
	v_cvt_pk_bf16_f32 v120, v3, v7
	v_mad_u64_u32 v[2:3], s[0:1], v2, s14, v[124:125]
	v_cvt_pk_bf16_f32 v121, v63, v67
	v_cvt_pk_bf16_f32 v122, v71, v109
	v_cvt_pk_bf16_f32 v123, v113, v117
	global_store_dwordx4 v[2:3], v[120:123], off
	v_or_b32_e32 v2, 2, v14
	v_mad_u64_u32 v[2:3], s[0:1], v2, s14, v[124:125]
	v_mad_u64_u32 v[6:7], s[0:1], v6, s14, v[124:125]
	v_cvt_pk_bf16_f32 v120, v4, v8
	v_cvt_pk_bf16_f32 v121, v64, v68
	v_cvt_pk_bf16_f32 v122, v72, v110
	v_cvt_pk_bf16_f32 v123, v114, v118
	global_store_dwordx4 v[2:3], v[120:123], off
	v_cvt_pk_bf16_f32 v2, v5, v9
	v_cvt_pk_bf16_f32 v3, v65, v69
	v_cvt_pk_bf16_f32 v4, v73, v111
	v_cvt_pk_bf16_f32 v5, v115, v119
	global_store_dwordx4 v[6:7], v[2:5], off
	s_waitcnt lgkmcnt(0)

; #define GAS __attribute__((address_space(1)))
; #define LAS __attribute__((address_space(3)))
; __device__ __forceinline__ void tr_item(const float* W, int K, int N, const float* gain, bf16* WT, int k0, int n0, int dstrow, LAS float* scr, int lane, float f8s) {
;     ...
;     for (int i = 0; i < 16; ++i) { const int kk = 4 * i + r0; f32x4 v = *(const GAS f32x4*)(W + (size_t)(k0 + kk) * N + n0 + 4 * c4); if (gain) v = v * gain[k0 + kk];
;         *(LAS f32x4*)(scr + kk * 64 + 4 * (c4 ^ (2 * ((kk >> 3) & 7)))) = v; }
.LBB0_171:
	v_lshl_add_u64 v[130:131], v[64:65], 0, s[4:5]
	global_load_dwordx4 v[140:143], v[130:131], off nt
	v_lshl_add_u64 v[130:131], v[70:71], 0, s[4:5]
	global_load_dwordx4 v[144:147], v[130:131], off nt
	v_lshl_add_u64 v[130:131], v[66:67], 0, s[4:5]
	global_load_dwordx4 v[148:151], v[130:131], off nt
	v_lshl_add_u64 v[130:131], v[62:63], 0, s[4:5]
	global_load_dwordx4 v[152:155], v[130:131], off nt
	v_cndmask_b32_e64 v2, 0, 1, s[30:31]
	v_cmp_ne_u32_e64 s[0:1], 1, v2
	v_add_u32_e32 v136, s17, v12
	v_bitop3_b32 v132, v136, v11, 56 bitop3:0x6c
	v_lshl_add_u32 v132, v132, 2, v14
	v_add_u32_e32 v133, 4, v136
	v_bitop3_b32 v133, v133, v11, 56 bitop3:0x6c
	v_lshl_add_u32 v133, v133, 2, v14
	v_add_u32_e32 v134, 8, v136
	v_bitop3_b32 v134, v134, v11, 56 bitop3:0x6c
	v_lshl_add_u32 v134, v134, 2, v14
	v_add_u32_e32 v135, 12, v136
	v_bitop3_b32 v135, v135, v11, 56 bitop3:0x6c
	v_lshl_add_u32 v135, v135, 2, v14
	s_andn2_b64 vcc, exec, s[30:31]
	s_cbranch_vccnz .Ltrg6_nog
	global_load_dword v156, v[68:69], off offset:-32
	global_load_dword v158, v[68:69], off offset:-16
	global_load_dword v160, v[68:69], off
	global_load_dword v162, v[68:69], off offset:16
	s_waitcnt vmcnt(0)
	v_pk_mul_f32 v[142:143], v[142:143], v[156:157] op_sel_hi:[1,0]
	v_pk_mul_f32 v[140:141], v[140:141], v[156:157] op_sel_hi:[1,0]
	v_pk_mul_f32 v[146:147], v[146:147], v[158:159] op_sel_hi:[1,0]
	v_pk_mul_f32 v[144:145], v[144:145], v[158:159] op_sel_hi:[1,0]
	v_pk_mul_f32 v[150:151], v[150:151], v[160:161] op_sel_hi:[1,0]
	v_pk_mul_f32 v[148:149], v[148:149], v[160:161] op_sel_hi:[1,0]
	v_pk_mul_f32 v[154:155], v[154:155], v[162:163] op_sel_hi:[1,0]
	v_pk_mul_f32 v[152:153], v[152:153], v[162:163] op_sel_hi:[1,0]
	s_branch .Ltrg6_wr

; #define GAS __attribute__((address_space(1)))
; #define LAS __attribute__((address_space(3)))
; __device__ __forceinline__ void tr_item(const float* W, int K, int N, const float* gain, bf16* WT, int k0, int n0, int dstrow, LAS float* scr, int lane, float f8s) {
;     ...
;     for (int i = 0; i < 16; ++i) { const int kk = 4 * i + r0; f32x4 v = *(const GAS f32x4*)(W + (size_t)(k0 + kk) * N + n0 + 4 * c4); if (gain) v = v * gain[k0 + kk];
;         *(LAS f32x4*)(scr + kk * 64 + 4 * (c4 ^ (2 * ((kk >> 3) & 7)))) = v; }
.LBB0_183:
	v_lshl_add_u64 v[130:131], v[64:65], 0, s[58:59]
	global_load_dwordx4 v[140:143], v[130:131], off nt
	v_lshl_add_u64 v[130:131], v[70:71], 0, s[58:59]
	global_load_dwordx4 v[144:147], v[130:131], off nt
	v_lshl_add_u64 v[130:131], v[66:67], 0, s[58:59]
	global_load_dwordx4 v[148:151], v[130:131], off nt
	v_lshl_add_u64 v[130:131], v[62:63], 0, s[58:59]
	global_load_dwordx4 v[152:155], v[130:131], off nt
	v_cndmask_b32_e64 v2, 0, 1, s[30:31]
	v_cmp_ne_u32_e64 s[0:1], 1, v2
	v_add_u32_e32 v136, s11, v12
	v_bitop3_b32 v132, v136, v11, 56 bitop3:0x6c
	v_lshl_add_u32 v132, v132, 2, v14
	v_add_u32_e32 v133, 4, v136
	v_bitop3_b32 v133, v133, v11, 56 bitop3:0x6c
	v_lshl_add_u32 v133, v133, 2, v14
	v_add_u32_e32 v134, 8, v136
	v_bitop3_b32 v134, v134, v11, 56 bitop3:0x6c
	v_lshl_add_u32 v134, v134, 2, v14
	v_add_u32_e32 v135, 12, v136
	v_bitop3_b32 v135, v135, v11, 56 bitop3:0x6c
	v_lshl_add_u32 v135, v135, 2, v14
	s_andn2_b64 vcc, exec, s[30:31]
	s_cbranch_vccnz .Ltrg7_nog
	global_load_dword v156, v[68:69], off offset:-32
	global_load_dword v158, v[68:69], off offset:-16
	global_load_dword v160, v[68:69], off
	global_load_dword v162, v[68:69], off offset:16
	s_waitcnt vmcnt(0)
	v_pk_mul_f32 v[142:143], v[142:143], v[156:157] op_sel_hi:[1,0]
	v_pk_mul_f32 v[140:141], v[140:141], v[156:157] op_sel_hi:[1,0]
	v_pk_mul_f32 v[146:147], v[146:147], v[158:159] op_sel_hi:[1,0]
	v_pk_mul_f32 v[144:145], v[144:145], v[158:159] op_sel_hi:[1,0]
	v_pk_mul_f32 v[150:151], v[150:151], v[160:161] op_sel_hi:[1,0]
	v_pk_mul_f32 v[148:149], v[148:149], v[160:161] op_sel_hi:[1,0]
	v_pk_mul_f32 v[154:155], v[154:155], v[162:163] op_sel_hi:[1,0]
	v_pk_mul_f32 v[152:153], v[152:153], v[162:163] op_sel_hi:[1,0]
	s_branch .Ltrg7_wr

; __device__ __forceinline__ unsigned cvt_pk_bf16(float lo, float hi) { unsigned r; asm volatile("v_cvt_pk_bf16_f32 %0, %1, %2" : "=v"(r) : "v"(lo), "v"(hi)); return r; }
; #define GAS __attribute__((address_space(1)))
; __device__ __forceinline__ void p0_prologue(const In& in, float* out, unsigned char* ws, LAS unsigned char* lds, int tid, int lane, int wave) {
;     ...
;     { bf16* XB = (bf16*)(ws + WS_XB); float* ss1 = (float*)(ws + WS_STAT) + ST_SS1 * MROWS;
;       for (int mm = gw; mm < MROWS * P0_REP; mm += NGW) { const int m = mm % MROWS; const GAS f32x4* xr = (const GAS f32x4*)(in.x + (size_t)m * DM) + lane; GAS v2u* o = (GAS v2u*)(XB + (size_t)m * DM) + lane; float s = 0.f;
; #pragma unroll
;           for (int j = 0; j < 8; ++j) { const f32x4 v = xr[64 * j]; s += (v.x * v.x + v.y * v.y) + (v.z * v.z + v.w * v.w); v2u w; w.x = cvt_pk_bf16(v.x, v.y); w.y = cvt_pk_bf16(v.z, v.w); o[64 * j] = w; }
;           s = wave_sum(s); if (lane == 0) ss1[m] = s; } }
.Lxb_norm:
	s_waitcnt lgkmcnt(0)
	s_lshl_b32 s3, s6, 13
	s_add_u32 s4, s52, s3
	s_addc_u32 s5, s53, 0
	s_add_u32 s4, s4, 0x1000
	s_addc_u32 s5, s5, 0
	global_load_dwordx4 v[16:19], v2, s[4:5] offset:-4096 nt
	global_load_dwordx4 v[20:23], v2, s[4:5] offset:-3072 nt
	global_load_dwordx4 v[24:27], v2, s[4:5] offset:-2048 nt
	global_load_dwordx4 v[28:31], v2, s[4:5] offset:-1024 nt
	global_load_dwordx4 v[32:35], v2, s[4:5] offset:0 nt
	global_load_dwordx4 v[36:39], v2, s[4:5] offset:1024 nt
	global_load_dwordx4 v[40:43], v2, s[4:5] offset:2048 nt
	global_load_dwordx4 v[44:47], v2, s[4:5] offset:3072 nt
	s_lshl_b32 s3, s6, 12
	s_add_u32 s8, s28, s3
	s_addc_u32 s9, s29, 0
	s_lshl_b32 s3, s6, 2
	s_add_u32 s12, s68, s3
	s_addc_u32 s13, s69, 0
	s_add_i32 s6, s6, s7
	s_cmp_gt_i32 s6, s10
	s_cbranch_scc1 .Lxb_last_f
	s_lshl_b32 s3, s6, 13
	s_add_u32 s4, s52, s3
	s_addc_u32 s5, s53, 0
	s_add_u32 s4, s4, 0x1000
	s_addc_u32 s5, s5, 0
	global_load_dwordx4 v[80:83], v2, s[4:5] offset:-4096 nt
	global_load_dwordx4 v[84:87], v2, s[4:5] offset:-3072 nt
	global_load_dwordx4 v[88:91], v2, s[4:5] offset:-2048 nt
	global_load_dwordx4 v[92:95], v2, s[4:5] offset:-1024 nt
	global_load_dwordx4 v[96:99], v2, s[4:5] offset:0 nt
	global_load_dwordx4 v[100:103], v2, s[4:5] offset:1024 nt
	global_load_dwordx4 v[104:107], v2, s[4:5] offset:2048 nt
	global_load_dwordx4 v[108:111], v2, s[4:5] offset:3072 nt
	s_waitcnt vmcnt(8)
	v_cvt_pk_bf16_f32 v48, v16, v17
	v_cvt_pk_bf16_f32 v49, v18, v19
	v_mul_f32_e32 v65, v17, v17
	v_mul_f32_e32 v66, v19, v19
	global_store_dwordx2 v3, v[48:49], s[8:9]
	v_fmac_f32_e32 v65, v16, v16
	v_fmac_f32_e32 v66, v18, v18
	v_add_f32_e32 v64, v65, v66
	v_cvt_pk_bf16_f32 v50, v20, v21
	v_cvt_pk_bf16_f32 v51, v22, v23
	v_mul_f32_e32 v65, v21, v21
	v_mul_f32_e32 v66, v23, v23
	global_store_dwordx2 v3, v[50:51], s[8:9] offset:512
	v_fmac_f32_e32 v65, v20, v20
	v_fmac_f32_e32 v66, v22, v22
	v_add_f32_e32 v65, v65, v66
	v_add_f32_e32 v64, v64, v65
	v_cvt_pk_bf16_f32 v52, v24, v25
	v_cvt_pk_bf16_f32 v53, v26, v27
	v_mul_f32_e32 v65, v25, v25
	v_mul_f32_e32 v66, v27, v27
	global_store_dwordx2 v3, v[52:53], s[8:9] offset:1024
	v_fmac_f32_e32 v65, v24, v24
	v_fmac_f32_e32 v66, v26, v26
	v_add_f32_e32 v65, v65, v66
	v_add_f32_e32 v64, v64, v65
	v_cvt_pk_bf16_f32 v54, v28, v29
	v_cvt_pk_bf16_f32 v55, v30, v31
	v_mul_f32_e32 v65, v29, v29
	v_mul_f32_e32 v66, v31, v31
	global_store_dwordx2 v3, v[54:55], s[8:9] offset:1536
	v_fmac_f32_e32 v65, v28, v28
	v_fmac_f32_e32 v66, v30, v30
	v_add_f32_e32 v65, v65, v66
	v_add_f32_e32 v64, v64, v65
	v_cvt_pk_bf16_f32 v56, v32, v33
	v_cvt_pk_bf16_f32 v57, v34, v35
	v_mul_f32_e32 v65, v33, v33
	v_mul_f32_e32 v66, v35, v35
	global_store_dwordx2 v3, v[56:57], s[8:9] offset:2048
	v_fmac_f32_e32 v65, v32, v32
	v_fmac_f32_e32 v66, v34, v34
	v_add_f32_e32 v65, v65, v66
	v_add_f32_e32 v64, v64, v65
	v_cvt_pk_bf16_f32 v58, v36, v37
	v_cvt_pk_bf16_f32 v59, v38, v39
	v_mul_f32_e32 v65, v37, v37
	v_mul_f32_e32 v66, v39, v39
	global_store_dwordx2 v3, v[58:59], s[8:9] offset:2560
	v_fmac_f32_e32 v65, v36, v36
	v_fmac_f32_e32 v66, v38, v38
	v_add_f32_e32 v65, v65, v66
	v_add_f32_e32 v64, v64, v65
	v_cvt_pk_bf16_f32 v60, v40, v41
	v_cvt_pk_bf16_f32 v61, v42, v43
	v_mul_f32_e32 v65, v41, v41
	v_mul_f32_e32 v66, v43, v43
	global_store_dwordx2 v3, v[60:61], s[8:9] offset:3072
	v_fmac_f32_e32 v65, v40, v40
	v_fmac_f32_e32 v66, v42, v42
	v_add_f32_e32 v65, v65, v66
	v_add_f32_e32 v64, v64, v65
	v_cvt_pk_bf16_f32 v62, v44, v45
	v_cvt_pk_bf16_f32 v63, v46, v47
	v_mul_f32_e32 v65, v45, v45
	v_mul_f32_e32 v66, v47, v47
	global_store_dwordx2 v3, v[62:63], s[8:9] offset:3584
	v_fmac_f32_e32 v65, v44, v44
	v_fmac_f32_e32 v66, v46, v46
	v_add_f32_e32 v65, v65, v66
	v_add_f32_e32 v64, v64, v65
	ds_bpermute_b32 v67, v68, v64
	s_waitcnt lgkmcnt(0)
	v_add_f32_e32 v64, v64, v67
	ds_bpermute_b32 v67, v69, v64
	s_waitcnt lgkmcnt(0)
	v_add_f32_e32 v64, v64, v67
	ds_bpermute_b32 v67, v70, v64
	s_waitcnt lgkmcnt(0)
	v_add_f32_e32 v64, v64, v67
	ds_bpermute_b32 v67, v71, v64
	s_waitcnt lgkmcnt(0)
	v_add_f32_e32 v64, v64, v67
	ds_bpermute_b32 v67, v72, v64
	s_waitcnt lgkmcnt(0)
	v_add_f32_e32 v64, v64, v67
	ds_bpermute_b32 v67, v73, v64
	s_waitcnt lgkmcnt(0)
	v_add_f32_e32 v64, v64, v67
	s_mov_b64 exec, 1
	global_store_dword v4, v64, s[12:13]
	s_mov_b64 exec, s[0:1]
	s_branch .Lxb_next_f

; __device__ __forceinline__ unsigned cvt_pk_bf16(float lo, float hi) { unsigned r; asm volatile("v_cvt_pk_bf16_f32 %0, %1, %2" : "=v"(r) : "v"(lo), "v"(hi)); return r; }
; #define GAS __attribute__((address_space(1)))
; __device__ __forceinline__ void p0_prologue(const In& in, float* out, unsigned char* ws, LAS unsigned char* lds, int tid, int lane, int wave) {
;     ...
;     { bf16* XB = (bf16*)(ws + WS_XB); float* ss1 = (float*)(ws + WS_STAT) + ST_SS1 * MROWS;
;       for (int mm = gw; mm < MROWS * P0_REP; mm += NGW) { const int m = mm % MROWS; const GAS f32x4* xr = (const GAS f32x4*)(in.x + (size_t)m * DM) + lane; GAS v2u* o = (GAS v2u*)(XB + (size_t)m * DM) + lane; float s = 0.f;
; #pragma unroll
;           for (int j = 0; j < 8; ++j) { const f32x4 v = xr[64 * j]; s += (v.x * v.x + v.y * v.y) + (v.z * v.z + v.w * v.w); v2u w; w.x = cvt_pk_bf16(v.x, v.y); w.y = cvt_pk_bf16(v.z, v.w); o[64 * j] = w; }
;           s = wave_sum(s); if (lane == 0) ss1[m] = s; } }
.Lxb_next_f:
.Lxb_loop:
	s_lshl_b32 s3, s6, 12
	s_add_u32 s8, s28, s3
	s_addc_u32 s9, s29, 0
	s_lshl_b32 s3, s6, 2
	s_add_u32 s12, s68, s3
	s_addc_u32 s13, s69, 0
	s_add_i32 s6, s6, s7
	s_cmp_gt_i32 s6, s10
	s_cbranch_scc1 .Lxb_last_b
	s_lshl_b32 s3, s6, 13
	s_add_u32 s4, s52, s3
	s_addc_u32 s5, s53, 0
	s_add_u32 s4, s4, 0x1000
	s_addc_u32 s5, s5, 0
	global_load_dwordx4 v[16:19], v2, s[4:5] offset:-4096 nt
	global_load_dwordx4 v[20:23], v2, s[4:5] offset:-3072 nt
	global_load_dwordx4 v[24:27], v2, s[4:5] offset:-2048 nt
	global_load_dwordx4 v[28:31], v2, s[4:5] offset:-1024 nt
	global_load_dwordx4 v[32:35], v2, s[4:5] offset:0 nt
	global_load_dwordx4 v[36:39], v2, s[4:5] offset:1024 nt
	global_load_dwordx4 v[40:43], v2, s[4:5] offset:2048 nt
	global_load_dwordx4 v[44:47], v2, s[4:5] offset:3072 nt
	s_waitcnt vmcnt(17)
	v_cvt_pk_bf16_f32 v48, v80, v81
	v_cvt_pk_bf16_f32 v49, v82, v83
	v_mul_f32_e32 v65, v81, v81
	v_mul_f32_e32 v66, v83, v83
	global_store_dwordx2 v3, v[48:49], s[8:9]
	v_fmac_f32_e32 v65, v80, v80
	v_fmac_f32_e32 v66, v82, v82
	v_add_f32_e32 v64, v65, v66
	v_cvt_pk_bf16_f32 v50, v84, v85
	v_cvt_pk_bf16_f32 v51, v86, v87
	v_mul_f32_e32 v65, v85, v85
	v_mul_f32_e32 v66, v87, v87
	global_store_dwordx2 v3, v[50:51], s[8:9] offset:512
	v_fmac_f32_e32 v65, v84, v84
	v_fmac_f32_e32 v66, v86, v86
	v_add_f32_e32 v65, v65, v66
	v_add_f32_e32 v64, v64, v65
	v_cvt_pk_bf16_f32 v52, v88, v89
	v_cvt_pk_bf16_f32 v53, v90, v91
	v_mul_f32_e32 v65, v89, v89
	v_mul_f32_e32 v66, v91, v91
	global_store_dwordx2 v3, v[52:53], s[8:9] offset:1024
	v_fmac_f32_e32 v65, v88, v88
	v_fmac_f32_e32 v66, v90, v90
	v_add_f32_e32 v65, v65, v66
	v_add_f32_e32 v64, v64, v65
	v_cvt_pk_bf16_f32 v54, v92, v93
	v_cvt_pk_bf16_f32 v55, v94, v95
	v_mul_f32_e32 v65, v93, v93
	v_mul_f32_e32 v66, v95, v95
	global_store_dwordx2 v3, v[54:55], s[8:9] offset:1536
	v_fmac_f32_e32 v65, v92, v92
	v_fmac_f32_e32 v66, v94, v94
	v_add_f32_e32 v65, v65, v66
	v_add_f32_e32 v64, v64, v65
	v_cvt_pk_bf16_f32 v56, v96, v97
	v_cvt_pk_bf16_f32 v57, v98, v99
	v_mul_f32_e32 v65, v97, v97
	v_mul_f32_e32 v66, v99, v99
	global_store_dwordx2 v3, v[56:57], s[8:9] offset:2048
	v_fmac_f32_e32 v65, v96, v96
	v_fmac_f32_e32 v66, v98, v98
	v_add_f32_e32 v65, v65, v66
	v_add_f32_e32 v64, v64, v65
	v_cvt_pk_bf16_f32 v58, v100, v101
	v_cvt_pk_bf16_f32 v59, v102, v103
	v_mul_f32_e32 v65, v101, v101
	v_mul_f32_e32 v66, v103, v103
	global_store_dwordx2 v3, v[58:59], s[8:9] offset:2560
	v_fmac_f32_e32 v65, v100, v100
	v_fmac_f32_e32 v66, v102, v102
	v_add_f32_e32 v65, v65, v66
	v_add_f32_e32 v64, v64, v65
	v_cvt_pk_bf16_f32 v60, v104, v105
	v_cvt_pk_bf16_f32 v61, v106, v107
	v_mul_f32_e32 v65, v105, v105
	v_mul_f32_e32 v66, v107, v107
	global_store_dwordx2 v3, v[60:61], s[8:9] offset:3072
	v_fmac_f32_e32 v65, v104, v104
	v_fmac_f32_e32 v66, v106, v106
	v_add_f32_e32 v65, v65, v66
	v_add_f32_e32 v64, v64, v65
	v_cvt_pk_bf16_f32 v62, v108, v109
	v_cvt_pk_bf16_f32 v63, v110, v111
	v_mul_f32_e32 v65, v109, v109
	v_mul_f32_e32 v66, v111, v111
	global_store_dwordx2 v3, v[62:63], s[8:9] offset:3584
	v_fmac_f32_e32 v65, v108, v108
	v_fmac_f32_e32 v66, v110, v110
	v_add_f32_e32 v65, v65, v66
	v_add_f32_e32 v64, v64, v65
	ds_bpermute_b32 v67, v68, v64
	s_waitcnt lgkmcnt(0)
	v_add_f32_e32 v64, v64, v67
	ds_bpermute_b32 v67, v69, v64
	s_waitcnt lgkmcnt(0)
	v_add_f32_e32 v64, v64, v67
	ds_bpermute_b32 v67, v70, v64
	s_waitcnt lgkmcnt(0)
	v_add_f32_e32 v64, v64, v67
	ds_bpermute_b32 v67, v71, v64
	s_waitcnt lgkmcnt(0)
	v_add_f32_e32 v64, v64, v67
	ds_bpermute_b32 v67, v72, v64
	s_waitcnt lgkmcnt(0)
	v_add_f32_e32 v64, v64, v67
	ds_bpermute_b32 v67, v73, v64
	s_waitcnt lgkmcnt(0)
	v_add_f32_e32 v64, v64, v67
	s_mov_b64 exec, 1
	global_store_dword v4, v64, s[12:13]
	s_mov_b64 exec, s[0:1]
	s_branch .Lxb_next_b

; __device__ __forceinline__ unsigned cvt_pk_bf16(float lo, float hi) { unsigned r; asm volatile("v_cvt_pk_bf16_f32 %0, %1, %2" : "=v"(r) : "v"(lo), "v"(hi)); return r; }
; #define GAS __attribute__((address_space(1)))
; __device__ __forceinline__ void p0_prologue(const In& in, float* out, unsigned char* ws, LAS unsigned char* lds, int tid, int lane, int wave) {
;     ...
;     { bf16* XB = (bf16*)(ws + WS_XB); float* ss1 = (float*)(ws + WS_STAT) + ST_SS1 * MROWS;
;       for (int mm = gw; mm < MROWS * P0_REP; mm += NGW) { const int m = mm % MROWS; const GAS f32x4* xr = (const GAS f32x4*)(in.x + (size_t)m * DM) + lane; GAS v2u* o = (GAS v2u*)(XB + (size_t)m * DM) + lane; float s = 0.f;
; #pragma unroll
;           for (int j = 0; j < 8; ++j) { const f32x4 v = xr[64 * j]; s += (v.x * v.x + v.y * v.y) + (v.z * v.z + v.w * v.w); v2u w; w.x = cvt_pk_bf16(v.x, v.y); w.y = cvt_pk_bf16(v.z, v.w); o[64 * j] = w; }
;           s = wave_sum(s); if (lane == 0) ss1[m] = s; } }
.Lxb_next_b:
	s_lshl_b32 s3, s6, 12
	s_add_u32 s8, s28, s3
	s_addc_u32 s9, s29, 0
	s_lshl_b32 s3, s6, 2
	s_add_u32 s12, s68, s3
	s_addc_u32 s13, s69, 0
	s_add_i32 s6, s6, s7
	s_cmp_gt_i32 s6, s10
	s_cbranch_scc1 .Lxb_last_a
	s_lshl_b32 s3, s6, 13
	s_add_u32 s4, s52, s3
	s_addc_u32 s5, s53, 0
	s_add_u32 s4, s4, 0x1000
	s_addc_u32 s5, s5, 0
	global_load_dwordx4 v[80:83], v2, s[4:5] offset:-4096 nt
	global_load_dwordx4 v[84:87], v2, s[4:5] offset:-3072 nt
	global_load_dwordx4 v[88:91], v2, s[4:5] offset:-2048 nt
	global_load_dwordx4 v[92:95], v2, s[4:5] offset:-1024 nt
	global_load_dwordx4 v[96:99], v2, s[4:5] offset:0 nt
	global_load_dwordx4 v[100:103], v2, s[4:5] offset:1024 nt
	global_load_dwordx4 v[104:107], v2, s[4:5] offset:2048 nt
	global_load_dwordx4 v[108:111], v2, s[4:5] offset:3072 nt
	s_waitcnt vmcnt(17)
	v_cvt_pk_bf16_f32 v48, v16, v17
	v_cvt_pk_bf16_f32 v49, v18, v19
	v_mul_f32_e32 v65, v17, v17
	v_mul_f32_e32 v66, v19, v19
	global_store_dwordx2 v3, v[48:49], s[8:9]
	v_fmac_f32_e32 v65, v16, v16
	v_fmac_f32_e32 v66, v18, v18
	v_add_f32_e32 v64, v65, v66
	v_cvt_pk_bf16_f32 v50, v20, v21
	v_cvt_pk_bf16_f32 v51, v22, v23
	v_mul_f32_e32 v65, v21, v21
	v_mul_f32_e32 v66, v23, v23
	global_store_dwordx2 v3, v[50:51], s[8:9] offset:512
	v_fmac_f32_e32 v65, v20, v20
	v_fmac_f32_e32 v66, v22, v22
	v_add_f32_e32 v65, v65, v66
	v_add_f32_e32 v64, v64, v65
	v_cvt_pk_bf16_f32 v52, v24, v25
	v_cvt_pk_bf16_f32 v53, v26, v27
	v_mul_f32_e32 v65, v25, v25
	v_mul_f32_e32 v66, v27, v27
	global_store_dwordx2 v3, v[52:53], s[8:9] offset:1024
	v_fmac_f32_e32 v65, v24, v24
	v_fmac_f32_e32 v66, v26, v26
	v_add_f32_e32 v65, v65, v66
	v_add_f32_e32 v64, v64, v65
	v_cvt_pk_bf16_f32 v54, v28, v29
	v_cvt_pk_bf16_f32 v55, v30, v31
	v_mul_f32_e32 v65, v29, v29
	v_mul_f32_e32 v66, v31, v31
	global_store_dwordx2 v3, v[54:55], s[8:9] offset:1536
	v_fmac_f32_e32 v65, v28, v28
	v_fmac_f32_e32 v66, v30, v30
	v_add_f32_e32 v65, v65, v66
	v_add_f32_e32 v64, v64, v65
	v_cvt_pk_bf16_f32 v56, v32, v33
	v_cvt_pk_bf16_f32 v57, v34, v35
	v_mul_f32_e32 v65, v33, v33
	v_mul_f32_e32 v66, v35, v35
	global_store_dwordx2 v3, v[56:57], s[8:9] offset:2048
	v_fmac_f32_e32 v65, v32, v32
	v_fmac_f32_e32 v66, v34, v34
	v_add_f32_e32 v65, v65, v66
	v_add_f32_e32 v64, v64, v65
	v_cvt_pk_bf16_f32 v58, v36, v37
	v_cvt_pk_bf16_f32 v59, v38, v39
	v_mul_f32_e32 v65, v37, v37
	v_mul_f32_e32 v66, v39, v39
	global_store_dwordx2 v3, v[58:59], s[8:9] offset:2560
	v_fmac_f32_e32 v65, v36, v36
	v_fmac_f32_e32 v66, v38, v38
	v_add_f32_e32 v65, v65, v66
	v_add_f32_e32 v64, v64, v65
	v_cvt_pk_bf16_f32 v60, v40, v41
	v_cvt_pk_bf16_f32 v61, v42, v43
	v_mul_f32_e32 v65, v41, v41
	v_mul_f32_e32 v66, v43, v43
	global_store_dwordx2 v3, v[60:61], s[8:9] offset:3072
	v_fmac_f32_e32 v65, v40, v40
	v_fmac_f32_e32 v66, v42, v42
	v_add_f32_e32 v65, v65, v66
	v_add_f32_e32 v64, v64, v65
	v_cvt_pk_bf16_f32 v62, v44, v45
	v_cvt_pk_bf16_f32 v63, v46, v47
	v_mul_f32_e32 v65, v45, v45
	v_mul_f32_e32 v66, v47, v47
	global_store_dwordx2 v3, v[62:63], s[8:9] offset:3584
	v_fmac_f32_e32 v65, v44, v44
	v_fmac_f32_e32 v66, v46, v46
	v_add_f32_e32 v65, v65, v66
	v_add_f32_e32 v64, v64, v65
	ds_bpermute_b32 v67, v68, v64
	s_waitcnt lgkmcnt(0)
	v_add_f32_e32 v64, v64, v67
	ds_bpermute_b32 v67, v69, v64
	s_waitcnt lgkmcnt(0)
	v_add_f32_e32 v64, v64, v67
	ds_bpermute_b32 v67, v70, v64
	s_waitcnt lgkmcnt(0)
	v_add_f32_e32 v64, v64, v67
	ds_bpermute_b32 v67, v71, v64
	s_waitcnt lgkmcnt(0)
	v_add_f32_e32 v64, v64, v67
	ds_bpermute_b32 v67, v72, v64
	s_waitcnt lgkmcnt(0)
	v_add_f32_e32 v64, v64, v67
	ds_bpermute_b32 v67, v73, v64
	s_waitcnt lgkmcnt(0)
	v_add_f32_e32 v64, v64, v67
	s_mov_b64 exec, 1
	global_store_dword v4, v64, s[12:13]
	s_mov_b64 exec, s[0:1]
	s_branch .Lxb_next_a

; __device__ __forceinline__ unsigned cvt_pk_bf16(float lo, float hi) { unsigned r; asm volatile("v_cvt_pk_bf16_f32 %0, %1, %2" : "=v"(r) : "v"(lo), "v"(hi)); return r; }
; #define GAS __attribute__((address_space(1)))
; __device__ __forceinline__ void p0_prologue(const In& in, float* out, unsigned char* ws, LAS unsigned char* lds, int tid, int lane, int wave) {
;     ...
;     { const GAS f32x4* ps = (const GAS f32x4*)in.p; GAS v2u* o = (GAS v2u*)(ws + WS_PB);
;       for (int i = bx * NTHREADS + tid; i < MROWS * PLE / 4; i += G * NTHREADS) { const f32x4 v = ps[i]; v2u w; w.x = cvt_pk_bf16(v.x, v.y); w.y = cvt_pk_bf16(v.z, v.w); o[i] = w; } }
.Lpb_batch:
	s_add_i32 s11, s3, s10
	s_cmpk_ge_i32 s11, 0x1000
	s_cbranch_scc1 .Lpb_tail
	global_load_dwordx4 v[16:19], v[4:5], off nt
	v_lshl_add_u64 v[4:5], v[4:5], 0, s[8:9]
	global_load_dwordx4 v[20:23], v[4:5], off nt
	v_lshl_add_u64 v[4:5], v[4:5], 0, s[8:9]
	global_load_dwordx4 v[24:27], v[4:5], off nt
	v_lshl_add_u64 v[4:5], v[4:5], 0, s[8:9]
	global_load_dwordx4 v[28:31], v[4:5], off nt
	v_lshl_add_u64 v[4:5], v[4:5], 0, s[8:9]
	global_load_dwordx4 v[32:35], v[4:5], off nt
	v_lshl_add_u64 v[4:5], v[4:5], 0, s[8:9]
	global_load_dwordx4 v[36:39], v[4:5], off nt
	v_lshl_add_u64 v[4:5], v[4:5], 0, s[8:9]
	global_load_dwordx4 v[40:43], v[4:5], off nt
	v_lshl_add_u64 v[4:5], v[4:5], 0, s[8:9]
	global_load_dwordx4 v[44:47], v[4:5], off nt
	v_lshl_add_u64 v[4:5], v[4:5], 0, s[8:9]
	s_waitcnt vmcnt(7)
	v_cvt_pk_bf16_f32 v48, v16, v17
	v_cvt_pk_bf16_f32 v49, v18, v19
	global_store_dwordx2 v[2:3], v[48:49], off
	v_lshl_add_u64 v[2:3], v[2:3], 0, s[6:7]
	s_waitcnt vmcnt(7)
	v_cvt_pk_bf16_f32 v50, v20, v21
	v_cvt_pk_bf16_f32 v51, v22, v23
	global_store_dwordx2 v[2:3], v[50:51], off
	v_lshl_add_u64 v[2:3], v[2:3], 0, s[6:7]
	s_waitcnt vmcnt(7)
	v_cvt_pk_bf16_f32 v52, v24, v25
	v_cvt_pk_bf16_f32 v53, v26, v27
	global_store_dwordx2 v[2:3], v[52:53], off
	v_lshl_add_u64 v[2:3], v[2:3], 0, s[6:7]
	s_waitcnt vmcnt(7)
	v_cvt_pk_bf16_f32 v54, v28, v29
	v_cvt_pk_bf16_f32 v55, v30, v31
	global_store_dwordx2 v[2:3], v[54:55], off
	v_lshl_add_u64 v[2:3], v[2:3], 0, s[6:7]
	s_waitcnt vmcnt(7)
	v_cvt_pk_bf16_f32 v56, v32, v33
	v_cvt_pk_bf16_f32 v57, v34, v35
	global_store_dwordx2 v[2:3], v[56:57], off
	v_lshl_add_u64 v[2:3], v[2:3], 0, s[6:7]
	s_waitcnt vmcnt(7)
	v_cvt_pk_bf16_f32 v58, v36, v37
	v_cvt_pk_bf16_f32 v59, v38, v39
	global_store_dwordx2 v[2:3], v[58:59], off
	v_lshl_add_u64 v[2:3], v[2:3], 0, s[6:7]
	s_waitcnt vmcnt(7)
	v_cvt_pk_bf16_f32 v60, v40, v41
	v_cvt_pk_bf16_f32 v61, v42, v43
	global_store_dwordx2 v[2:3], v[60:61], off
	v_lshl_add_u64 v[2:3], v[2:3], 0, s[6:7]
	s_waitcnt vmcnt(7)
	v_cvt_pk_bf16_f32 v62, v44, v45
	v_cvt_pk_bf16_f32 v63, v46, v47
	global_store_dwordx2 v[2:3], v[62:63], off
	v_lshl_add_u64 v[2:3], v[2:3], 0, s[6:7]
	s_lshl_b32 s11, s12, 3
	s_add_i32 s3, s3, s11
	s_branch .Lpb_batch
.Lpb_tail:
	s_cmpk_ge_i32 s3, 0x1000
	s_cbranch_scc1 .LBB0_199
	global_load_dwordx4 v[16:19], v[4:5], off nt
	v_lshl_add_u64 v[4:5], v[4:5], 0, s[8:9]
	s_add_i32 s3, s3, s12
	s_waitcnt vmcnt(0)
	v_cvt_pk_bf16_f32 v48, v16, v17
	v_cvt_pk_bf16_f32 v49, v18, v19
	global_store_dwordx2 v[2:3], v[48:49], off
	v_lshl_add_u64 v[2:3], v[2:3], 0, s[6:7]
	s_branch .Lpb_tail
